# P2 tile order: each workgroup's four column tiles permuted so the three slow-epilogue (V^T) tiles land in different workgroup classes and the last round has only light epilogues
# speedup vs baseline: 1.0007x; 1.0007x over previous
.LBB0_417:
	s_ashr_i32 s14, s20, 3
	s_add_i32 s14, s22, s14
	s_ashr_i32 s15, s14, 31
	s_lshr_b32 s15, s15, 25
	s_add_i32 s15, s14, s15
	s_ashr_i32 s20, s15, 7
	s_lshl_b32 s20, s20, 3
	s_sub_i32 s21, 64, s20
	s_min_i32 s21, s21, 8
	s_abs_i32 s22, s21
	v_cvt_f32_u32_e32 v0, s22
	s_sub_i32 s24, 0, s22
	s_and_b32 s15, s15, 0xffffff80
	s_sub_i32 s14, s14, s15
	v_rcp_iflag_f32_e32 v0, v0
	s_abs_i32 s15, s14
	s_xor_b32 s23, s14, s21
	s_ashr_i32 s23, s23, 31
	v_mul_f32_e32 v0, 0x4f7ffffe, v0
	v_cvt_u32_f32_e32 v0, v0
	s_nop 0
	v_readfirstlane_b32 s25, v0
	s_mul_i32 s24, s24, s25
	s_mul_hi_u32 s24, s25, s24
	s_add_i32 s25, s25, s24
	s_mul_hi_u32 s24, s15, s25
	s_mul_i32 s25, s24, s22
	s_sub_i32 s15, s15, s25
	s_add_i32 s35, s24, 1
	s_sub_i32 s25, s15, s22
	s_cmp_ge_u32 s15, s22
	s_cselect_b32 s24, s35, s24
	s_cselect_b32 s15, s25, s15
	s_add_i32 s25, s24, 1
	s_cmp_ge_u32 s15, s22
	s_cselect_b32 s15, s25, s24
	s_xor_b32 s15, s15, s23
	s_sub_i32 s38, s15, s23
	s_mul_i32 s15, s38, s21
	s_sub_i32 s14, s14, s15
	s_add_i32 s64, s20, s14
	s_lshl_b32 s20, s38, 2
	s_mov_b32 s14, 0xD9543210
	s_mov_b32 s15, 0xFB87EA6C
	s_lshr_b64 s[14:15], s[14:15], s20
	s_and_b32 s38, s14, 15
	s_ashr_i32 s65, s64, 31
	s_lshl_b64 s[14:15], s[64:65], 19
	v_readlane_b32 s20, v254, 61
	s_add_u32 s96, s20, s14
	v_readlane_b32 s14, v254, 63
	s_addc_u32 s97, s14, s15
	s_ashr_i32 s39, s38, 31
	s_lshl_b64 s[14:15], s[38:39], 19
	v_readlane_b32 s20, v255, 1
	s_add_u32 s94, s20, s14
	v_readlane_b32 s14, v255, 3
	s_addc_u32 s95, s14, s15
